# two-block barrier intervals with waves 4-7 starting each interval 192 cycles later
# speedup vs baseline: 1.0082x; 1.0082x over previous
; template <int MODE> ...
;     ...
;     for (int jA = j0, pp = 0; jA <= qb; jA += 2, pp ^= 1) {
;       for (int sub = 0; sub < 2; ++sub) {
;         const int j = jA + sub; if (j > qb) break;
;         const bool pre = j + 2 <= qb;
;         if (pre) NSA_LD1(j + 2);
;         const LAS bf16_t* Ks = stage + pp * 18432 + sub * 9216; const LAS bf16_t* Vs = Ks + 4608;
;         const bool far = MODE == 0 && (qb - j >= 17);
; #pragma unroll
;         for (int tile = 0; tile < 2; ++tile) {
;             const int tl0 = wave * 8 + tile * 4, t0 = qb * 64 + tl0;
;             unsigned mb[4] = {1u, 1u, 1u, 1u};
;             if (MODE == 0) {
; #pragma unroll
;                 for (int i = 0; i < 4; ++i) mb[i] = (masks[(tl0 + i) * 4 + (j >> 5)] >> (j & 31)) & 1u; }
;             if (MODE == 1 || __builtin_amdgcn_readfirstlane((int)(mb[0] | mb[1] | mb[2] | mb[3]))) {
;                 f32x4 sc[4];
; #pragma unroll
;                 for (int cc = 0; cc < 4; ++cc) { const LAS bf16_t* kp = Ks + (cc * 16 + r16) * 72 + q4 * 8;
;                     sc[cc] = MFMA16(aq[tile][0], *(const LAS bf16x8*)kp, z4); sc[cc] = MFMA16(aq[tile][1], *(const LAS bf16x8*)(kp + 32), sc[cc]); }
;                 if (far) {
; #pragma unroll
;                     for (int cc = 0; cc < 4; ++cc)
; #pragma unroll
;                         for (int i = 0; i < 4; ++i) { const float p = mb[i] ? ex2(sc[cc][i] + bfar) : 0.f; ls[tile][i] += p; Pb[(4 * q4 + i) * 72 + cc * 16 + r16] = tobf(p); }
;                 } else {
; #pragma unroll
;                     for (int cc = 0; cc < 4; ++cc) { const int pos = j * 64 + cc * 16 + r16;
; #pragma unroll
;                         for (int i = 0; i < 4; ++i) { const int dist = t0 + i - pos; const bool ok = MODE ? ((unsigned)dist < 512u) : (dist >= 0 && mb[i]);
;                             const float p = ok ? ex2(sc[cc][i] + bt[clampd(dist)]) : 0.f; ls[tile][i] += p; Pb[(4 * q4 + i) * 72 + cc * 16 + r16] = tobf(p); } }
;                 }
;                 CBAR();
; #pragma unroll
;                 for (int ks = 0; ks < 2; ++ks) { const bf16x8 aP = *(const LAS bf16x8*)(Pb + r16 * 72 + ks * 32 + q4 * 8);
; #pragma unroll
;                     for (int nt = 0; nt < 4; ++nt) os[tile][nt] = MFMA16(aP, *(const LAS bf16x8*)(Vs + (nt * 16 + r16) * 72 + ks * 32 + q4 * 8), os[tile][nt]); }
;                 CBAR();
;             }
;         }
.Lnsa_pbar_27:
	s_waitcnt vmcnt(0) lgkmcnt(0)
	s_barrier
	s_cmp_lt_u32 s80, 32
	s_cbranch_scc1 .Lnsa_nostag_29
	s_sleep 3
